# RWKV scan rewrite (8 compute waves, f32 k/r staged in LDS, 2-chunk-ahead prefetch) plus S5 scan inner loops rescheduled: 4 tokens interleaved, 2-op complex recurrence
# speedup vs baseline: 1.0042x; 1.0042x over previous
; DI void s5_item(const PRef& p, int l, int b, int g) {
;     ...
;     for (int tt = 0; tt < 16; ++tt) {
;       float bur = 0.f, bui = 0.f;
; #pragma unroll
;       for (int h4 = 0; h4 < 4; ++h4) {
;         float4 u = *reinterpret_cast<const float4*>(uw + tt * 16 + h4 * 4);
;         bur += Bre[h4 * 4] * u.x + Bre[h4 * 4 + 1] * u.y + Bre[h4 * 4 + 2] * u.z + Bre[h4 * 4 + 3] * u.w;
;         bui += Bim[h4 * 4] * u.x + Bim[h4 * 4 + 1] * u.y + Bim[h4 * 4 + 2] * u.z + Bim[h4 * 4 + 3] * u.w;
;       }
;       float nr = cr * xr - ci * xi + bur, ni = cr * xi + ci * xr + bui;
;       xr = nr; xi = ni;
.LBB0_222:
	v_add_u32_e32 v85, s6, v78
	ds_read_b128 v[130:133], v85 offset:0
	ds_read_b128 v[146:149], v85 offset:64
	ds_read_b128 v[162:165], v85 offset:128
	ds_read_b128 v[178:181], v85 offset:192
	ds_read_b128 v[134:137], v85 offset:16
	ds_read_b128 v[150:153], v85 offset:80
	ds_read_b128 v[166:169], v85 offset:144
	ds_read_b128 v[182:185], v85 offset:208
	s_waitcnt lgkmcnt(4)
	ds_read_b128 v[138:141], v85 offset:32
	ds_read_b128 v[154:157], v85 offset:96
	ds_read_b128 v[170:173], v85 offset:160
	ds_read_b128 v[186:189], v85 offset:224
	v_pk_mul_f32 v[194:195], v[38:39], v[130:131]
	v_pk_mul_f32 v[196:197], v[38:39], v[146:147]
	v_pk_mul_f32 v[198:199], v[38:39], v[162:163]
	v_pk_mul_f32 v[200:201], v[38:39], v[178:179]
	v_pk_fma_f32 v[194:195], v[36:37], v[130:131], v[194:195] op_sel:[0,1,0] op_sel_hi:[1,0,1]
	v_pk_fma_f32 v[196:197], v[36:37], v[146:147], v[196:197] op_sel:[0,1,0] op_sel_hi:[1,0,1]
	v_pk_fma_f32 v[198:199], v[36:37], v[162:163], v[198:199] op_sel:[0,1,0] op_sel_hi:[1,0,1]
	v_pk_fma_f32 v[200:201], v[36:37], v[178:179], v[200:201] op_sel:[0,1,0] op_sel_hi:[1,0,1]
	v_pk_fma_f32 v[194:195], v[40:41], v[132:133], v[194:195] op_sel_hi:[1,0,1]
	v_pk_fma_f32 v[196:197], v[40:41], v[148:149], v[196:197] op_sel_hi:[1,0,1]
	v_pk_fma_f32 v[198:199], v[40:41], v[164:165], v[198:199] op_sel_hi:[1,0,1]
	v_pk_fma_f32 v[200:201], v[40:41], v[180:181], v[200:201] op_sel_hi:[1,0,1]
	v_pk_fma_f32 v[194:195], v[42:43], v[132:133], v[194:195] op_sel:[0,1,0] op_sel_hi:[1,1,1]
	v_pk_fma_f32 v[196:197], v[42:43], v[148:149], v[196:197] op_sel:[0,1,0] op_sel_hi:[1,1,1]
	v_pk_fma_f32 v[198:199], v[42:43], v[164:165], v[198:199] op_sel:[0,1,0] op_sel_hi:[1,1,1]
	v_pk_fma_f32 v[200:201], v[42:43], v[180:181], v[200:201] op_sel:[0,1,0] op_sel_hi:[1,1,1]
	s_waitcnt lgkmcnt(4)
	ds_read_b128 v[142:145], v85 offset:48
	ds_read_b128 v[158:161], v85 offset:112
	ds_read_b128 v[174:177], v85 offset:176
	ds_read_b128 v[190:193], v85 offset:240
	v_pk_fma_f32 v[194:195], v[46:47], v[134:135], v[194:195]
	v_pk_fma_f32 v[196:197], v[46:47], v[150:151], v[196:197]
	v_pk_fma_f32 v[198:199], v[46:47], v[166:167], v[198:199]
	v_pk_fma_f32 v[200:201], v[46:47], v[182:183], v[200:201]
	v_pk_fma_f32 v[194:195], v[44:45], v[134:135], v[194:195] op_sel:[0,1,0] op_sel_hi:[1,0,1]
	v_pk_fma_f32 v[196:197], v[44:45], v[150:151], v[196:197] op_sel:[0,1,0] op_sel_hi:[1,0,1]
	v_pk_fma_f32 v[198:199], v[44:45], v[166:167], v[198:199] op_sel:[0,1,0] op_sel_hi:[1,0,1]
	v_pk_fma_f32 v[200:201], v[44:45], v[182:183], v[200:201] op_sel:[0,1,0] op_sel_hi:[1,0,1]
	v_pk_fma_f32 v[194:195], v[48:49], v[136:137], v[194:195] op_sel_hi:[1,0,1]
	v_pk_fma_f32 v[196:197], v[48:49], v[152:153], v[196:197] op_sel_hi:[1,0,1]
	v_pk_fma_f32 v[198:199], v[48:49], v[168:169], v[198:199] op_sel_hi:[1,0,1]
	v_pk_fma_f32 v[200:201], v[48:49], v[184:185], v[200:201] op_sel_hi:[1,0,1]
	v_pk_fma_f32 v[194:195], v[50:51], v[136:137], v[194:195] op_sel:[0,1,0] op_sel_hi:[1,1,1]
	v_pk_fma_f32 v[196:197], v[50:51], v[152:153], v[196:197] op_sel:[0,1,0] op_sel_hi:[1,1,1]
	v_pk_fma_f32 v[198:199], v[50:51], v[168:169], v[198:199] op_sel:[0,1,0] op_sel_hi:[1,1,1]
	v_pk_fma_f32 v[200:201], v[50:51], v[184:185], v[200:201] op_sel:[0,1,0] op_sel_hi:[1,1,1]
	s_waitcnt lgkmcnt(4)
	v_pk_fma_f32 v[194:195], v[54:55], v[138:139], v[194:195]
	v_pk_fma_f32 v[196:197], v[54:55], v[154:155], v[196:197]
	v_pk_fma_f32 v[198:199], v[54:55], v[170:171], v[198:199]
	v_pk_fma_f32 v[200:201], v[54:55], v[186:187], v[200:201]
	v_pk_fma_f32 v[194:195], v[52:53], v[138:139], v[194:195] op_sel:[0,1,0] op_sel_hi:[1,0,1]
	v_pk_fma_f32 v[196:197], v[52:53], v[154:155], v[196:197] op_sel:[0,1,0] op_sel_hi:[1,0,1]
	v_pk_fma_f32 v[198:199], v[52:53], v[170:171], v[198:199] op_sel:[0,1,0] op_sel_hi:[1,0,1]
	v_pk_fma_f32 v[200:201], v[52:53], v[186:187], v[200:201] op_sel:[0,1,0] op_sel_hi:[1,0,1]
	v_pk_fma_f32 v[194:195], v[56:57], v[140:141], v[194:195] op_sel_hi:[1,0,1]
	v_pk_fma_f32 v[196:197], v[56:57], v[156:157], v[196:197] op_sel_hi:[1,0,1]
	v_pk_fma_f32 v[198:199], v[56:57], v[172:173], v[198:199] op_sel_hi:[1,0,1]
	v_pk_fma_f32 v[200:201], v[56:57], v[188:189], v[200:201] op_sel_hi:[1,0,1]
	v_pk_fma_f32 v[194:195], v[58:59], v[140:141], v[194:195] op_sel:[0,1,0] op_sel_hi:[1,1,1]
	v_pk_fma_f32 v[196:197], v[58:59], v[156:157], v[196:197] op_sel:[0,1,0] op_sel_hi:[1,1,1]
	v_pk_fma_f32 v[198:199], v[58:59], v[172:173], v[198:199] op_sel:[0,1,0] op_sel_hi:[1,1,1]
	v_pk_fma_f32 v[200:201], v[58:59], v[188:189], v[200:201] op_sel:[0,1,0] op_sel_hi:[1,1,1]
	s_waitcnt lgkmcnt(0)
	v_pk_fma_f32 v[194:195], v[62:63], v[142:143], v[194:195]
	v_pk_fma_f32 v[196:197], v[62:63], v[158:159], v[196:197]
	v_pk_fma_f32 v[198:199], v[62:63], v[174:175], v[198:199]
	v_pk_fma_f32 v[200:201], v[62:63], v[190:191], v[200:201]
	v_pk_fma_f32 v[194:195], v[60:61], v[142:143], v[194:195] op_sel:[0,1,0] op_sel_hi:[1,0,1]
	v_pk_fma_f32 v[196:197], v[60:61], v[158:159], v[196:197] op_sel:[0,1,0] op_sel_hi:[1,0,1]
	v_pk_fma_f32 v[198:199], v[60:61], v[174:175], v[198:199] op_sel:[0,1,0] op_sel_hi:[1,0,1]
	v_pk_fma_f32 v[200:201], v[60:61], v[190:191], v[200:201] op_sel:[0,1,0] op_sel_hi:[1,0,1]
	v_pk_fma_f32 v[194:195], v[64:65], v[144:145], v[194:195] op_sel_hi:[1,0,1]
	v_pk_fma_f32 v[196:197], v[64:65], v[160:161], v[196:197] op_sel_hi:[1,0,1]
	v_pk_fma_f32 v[198:199], v[64:65], v[176:177], v[198:199] op_sel_hi:[1,0,1]
	v_pk_fma_f32 v[200:201], v[64:65], v[192:193], v[200:201] op_sel_hi:[1,0,1]
	v_pk_fma_f32 v[194:195], v[66:67], v[144:145], v[194:195] op_sel:[0,1,0] op_sel_hi:[1,1,1]
	v_pk_fma_f32 v[196:197], v[66:67], v[160:161], v[196:197] op_sel:[0,1,0] op_sel_hi:[1,1,1]
	v_pk_fma_f32 v[198:199], v[66:67], v[176:177], v[198:199] op_sel:[0,1,0] op_sel_hi:[1,1,1]
	v_pk_fma_f32 v[200:201], v[66:67], v[192:193], v[200:201] op_sel:[0,1,0] op_sel_hi:[1,1,1]
	v_pk_fma_f32 v[202:203], v[70:71], v[72:73], v[194:195] op_sel:[0,1,0] op_sel_hi:[1,1,1] neg_lo:[1,0,0]
	s_nop 0
	v_pk_fma_f32 v[72:73], v[34:35], v[72:73], v[202:203] op_sel_hi:[1,0,1]
	s_nop 0
	v_pk_fma_f32 v[202:203], v[70:71], v[72:73], v[196:197] op_sel:[0,1,0] op_sel_hi:[1,1,1] neg_lo:[1,0,0]
	s_nop 0
	v_pk_fma_f32 v[72:73], v[34:35], v[72:73], v[202:203] op_sel_hi:[1,0,1]
	s_nop 0
	v_pk_fma_f32 v[202:203], v[70:71], v[72:73], v[198:199] op_sel:[0,1,0] op_sel_hi:[1,1,1] neg_lo:[1,0,0]
	s_nop 0
	v_pk_fma_f32 v[72:73], v[34:35], v[72:73], v[202:203] op_sel_hi:[1,0,1]
	s_nop 0
	v_pk_fma_f32 v[202:203], v[70:71], v[72:73], v[200:201] op_sel:[0,1,0] op_sel_hi:[1,1,1] neg_lo:[1,0,0]
	s_nop 0
	v_pk_fma_f32 v[72:73], v[34:35], v[72:73], v[202:203] op_sel_hi:[1,0,1]
	s_nop 0
	s_addk_i32 s6, 0x100
	s_cmpk_lg_i32 s6, 0x400
	s_cbranch_scc1 .LBB0_222
; DI void s5_item(const PRef& p, int l, int b, int g) {
;     ...
;   }
;   fin[(w * 64 + lane) * 2] = xr; fin[(w * 64 + lane) * 2 + 1] = xi;
;   __syncthreads();
;   {
;     float pr = cr, pi = ci;
;     for (int i = 0; i < 9; ++i) { float nr = pr * pr - pi * pi, ni = 2.f * pr * pi; pr = nr; pi = ni; }
;     float vr = 0.f, vi = 0.f;
;     for (int ww = 0; ww < w; ++ww) {
;       float fr_ = fin[(ww * 64 + lane) * 2], fi_ = fin[(ww * 64 + lane) * 2 + 1];
;       float nr = pr * vr - pi * vi + fr_, ni = pr * vi + pi * vr + fi_;
;       vr = nr; vi = ni;
;     }
;     xr = vr; xi = vi;
;   }
	s_add_i32 s27, s27, 1
	s_cmp_eq_u32 s27, 32
	s_cbranch_scc0 .LBB0_221
	v_lshl_add_u32 v16, v74, 3, 16
	v_cmp_gt_i32_e32 vcc, 1, v81
	v_lshlrev_b32_e32 v85, 3, v75
	ds_write_b64 v16, v[72:73] offset:8192
	s_waitcnt lgkmcnt(0)
	s_barrier
	s_and_saveexec_b64 s[6:7], vcc
	s_xor_b64 s[6:7], exec, s[6:7]
	v_lshlrev_b32_e32 v85, 3, v75
	s_or_saveexec_b64 s[6:7], s[6:7]
	v_mov_b32_e32 v16, v17
	v_mov_b64_e32 v[72:73], v[16:17]
	s_xor_b64 exec, exec, s[6:7]
	s_cbranch_execz .LBB0_230
	v_pk_mul_f32 v[72:73], v[34:35], v[34:35]
	v_add_f32_e32 v16, v34, v34
	v_sub_f32_e32 v72, v72, v73
	v_mul_f32_e32 v16, v35, v16
	v_add_f32_e32 v73, v72, v72
	v_mul_f32_e32 v72, v72, v72
	v_mul_f32_e32 v73, v16, v73
	v_fma_f32 v16, -v16, v16, v72
	v_add_f32_e32 v72, v16, v16
	v_mul_f32_e32 v72, v73, v72
	v_mul_f32_e32 v73, v73, v73
	v_fma_f32 v16, v16, v16, -v73
	v_add_f32_e32 v73, v16, v16
	v_mul_f32_e32 v73, v72, v73
	v_mul_f32_e32 v72, v72, v72
	v_fma_f32 v16, v16, v16, -v72
	v_add_f32_e32 v72, v16, v16
	v_mul_f32_e32 v72, v73, v72
	v_mul_f32_e32 v73, v73, v73
	v_fma_f32 v16, v16, v16, -v73
	v_add_f32_e32 v73, v16, v16
	v_mul_f32_e32 v73, v72, v73
	v_mul_f32_e32 v72, v72, v72
	v_fma_f32 v16, v16, v16, -v72
	v_add_f32_e32 v72, v16, v16
	v_mul_f32_e32 v72, v73, v72
	v_mul_f32_e32 v73, v73, v73
	v_fma_f32 v16, v16, v16, -v73
	v_add_f32_e32 v73, v16, v16
	v_mul_f32_e32 v73, v72, v73
	v_mul_f32_e32 v72, v72, v72
	v_fma_f32 v16, v16, v16, -v72
	v_add_f32_e32 v72, v16, v16
	v_mul_f32_e32 v74, v73, v72
	v_mul_f32_e32 v72, v73, v73
	v_fma_f32 v76, v16, v16, -v72
	s_add_i32 s8, 16, 0x2000
	v_mov_b32_e32 v72, 0
	v_mov_b32_e32 v77, v76
	v_mov_b32_e32 v75, v74
	v_add_u32_e32 v16, s8, v85
	s_mov_b64 s[8:9], 0
	v_mov_b32_e32 v86, v81
	v_mov_b32_e32 v73, v72

; DI void s5_item(const PRef& p, int l, int b, int g) {
;     ...
;     for (int tt = 0; tt < 16; ++tt) {
;       float bur = 0.f, bui = 0.f;
; #pragma unroll
;       for (int h4 = 0; h4 < 4; ++h4) {
;         float4 u = *reinterpret_cast<const float4*>(uw + tt * 16 + h4 * 4);
;         bur += Bre[h4 * 4] * u.x + Bre[h4 * 4 + 1] * u.y + Bre[h4 * 4 + 2] * u.z + Bre[h4 * 4 + 3] * u.w;
;         bui += Bim[h4 * 4] * u.x + Bim[h4 * 4 + 1] * u.y + Bim[h4 * 4 + 2] * u.z + Bim[h4 * 4 + 3] * u.w;
;       }
;       float nr = cr * xr - ci * xi + bur, ni = cr * xi + ci * xr + bui;
;       xr = nr; xi = ni;
;       *reinterpret_cast<float2*>(xw + (tt * 66 + lane) * 2) = make_float2(xr, xi);
;     }
.LBB0_233:
	v_add_u32_e32 v23, s2, v78
	ds_read_b128 v[130:133], v23 offset:0
	ds_read_b128 v[146:149], v23 offset:64
	ds_read_b128 v[162:165], v23 offset:128
	ds_read_b128 v[178:181], v23 offset:192
	ds_read_b128 v[134:137], v23 offset:16
	ds_read_b128 v[150:153], v23 offset:80
	ds_read_b128 v[166:169], v23 offset:144
	ds_read_b128 v[182:185], v23 offset:208
	s_waitcnt lgkmcnt(4)
	ds_read_b128 v[138:141], v23 offset:32
	ds_read_b128 v[154:157], v23 offset:96
	ds_read_b128 v[170:173], v23 offset:160
	ds_read_b128 v[186:189], v23 offset:224
	v_pk_mul_f32 v[194:195], v[38:39], v[130:131]
	v_pk_mul_f32 v[196:197], v[38:39], v[146:147]
	v_pk_mul_f32 v[198:199], v[38:39], v[162:163]
	v_pk_mul_f32 v[200:201], v[38:39], v[178:179]
	v_pk_fma_f32 v[194:195], v[36:37], v[130:131], v[194:195] op_sel:[0,1,0] op_sel_hi:[1,0,1]
	v_pk_fma_f32 v[196:197], v[36:37], v[146:147], v[196:197] op_sel:[0,1,0] op_sel_hi:[1,0,1]
	v_pk_fma_f32 v[198:199], v[36:37], v[162:163], v[198:199] op_sel:[0,1,0] op_sel_hi:[1,0,1]
	v_pk_fma_f32 v[200:201], v[36:37], v[178:179], v[200:201] op_sel:[0,1,0] op_sel_hi:[1,0,1]
	v_pk_fma_f32 v[194:195], v[40:41], v[132:133], v[194:195] op_sel_hi:[1,0,1]
	v_pk_fma_f32 v[196:197], v[40:41], v[148:149], v[196:197] op_sel_hi:[1,0,1]
	v_pk_fma_f32 v[198:199], v[40:41], v[164:165], v[198:199] op_sel_hi:[1,0,1]
	v_pk_fma_f32 v[200:201], v[40:41], v[180:181], v[200:201] op_sel_hi:[1,0,1]
	v_pk_fma_f32 v[194:195], v[42:43], v[132:133], v[194:195] op_sel:[0,1,0] op_sel_hi:[1,1,1]
	v_pk_fma_f32 v[196:197], v[42:43], v[148:149], v[196:197] op_sel:[0,1,0] op_sel_hi:[1,1,1]
	v_pk_fma_f32 v[198:199], v[42:43], v[164:165], v[198:199] op_sel:[0,1,0] op_sel_hi:[1,1,1]
	v_pk_fma_f32 v[200:201], v[42:43], v[180:181], v[200:201] op_sel:[0,1,0] op_sel_hi:[1,1,1]
	s_waitcnt lgkmcnt(4)
	ds_read_b128 v[142:145], v23 offset:48
	ds_read_b128 v[158:161], v23 offset:112
	ds_read_b128 v[174:177], v23 offset:176
	ds_read_b128 v[190:193], v23 offset:240
	v_pk_fma_f32 v[194:195], v[46:47], v[134:135], v[194:195]
	v_pk_fma_f32 v[196:197], v[46:47], v[150:151], v[196:197]
	v_pk_fma_f32 v[198:199], v[46:47], v[166:167], v[198:199]
	v_pk_fma_f32 v[200:201], v[46:47], v[182:183], v[200:201]
	v_pk_fma_f32 v[194:195], v[44:45], v[134:135], v[194:195] op_sel:[0,1,0] op_sel_hi:[1,0,1]
	v_pk_fma_f32 v[196:197], v[44:45], v[150:151], v[196:197] op_sel:[0,1,0] op_sel_hi:[1,0,1]
	v_pk_fma_f32 v[198:199], v[44:45], v[166:167], v[198:199] op_sel:[0,1,0] op_sel_hi:[1,0,1]
	v_pk_fma_f32 v[200:201], v[44:45], v[182:183], v[200:201] op_sel:[0,1,0] op_sel_hi:[1,0,1]
	v_pk_fma_f32 v[194:195], v[48:49], v[136:137], v[194:195] op_sel_hi:[1,0,1]
	v_pk_fma_f32 v[196:197], v[48:49], v[152:153], v[196:197] op_sel_hi:[1,0,1]
	v_pk_fma_f32 v[198:199], v[48:49], v[168:169], v[198:199] op_sel_hi:[1,0,1]
	v_pk_fma_f32 v[200:201], v[48:49], v[184:185], v[200:201] op_sel_hi:[1,0,1]
	v_pk_fma_f32 v[194:195], v[50:51], v[136:137], v[194:195] op_sel:[0,1,0] op_sel_hi:[1,1,1]
	v_pk_fma_f32 v[196:197], v[50:51], v[152:153], v[196:197] op_sel:[0,1,0] op_sel_hi:[1,1,1]
	v_pk_fma_f32 v[198:199], v[50:51], v[168:169], v[198:199] op_sel:[0,1,0] op_sel_hi:[1,1,1]
	v_pk_fma_f32 v[200:201], v[50:51], v[184:185], v[200:201] op_sel:[0,1,0] op_sel_hi:[1,1,1]
	s_waitcnt lgkmcnt(4)
	v_pk_fma_f32 v[194:195], v[54:55], v[138:139], v[194:195]
	v_pk_fma_f32 v[196:197], v[54:55], v[154:155], v[196:197]
	v_pk_fma_f32 v[198:199], v[54:55], v[170:171], v[198:199]
	v_pk_fma_f32 v[200:201], v[54:55], v[186:187], v[200:201]
	v_pk_fma_f32 v[194:195], v[52:53], v[138:139], v[194:195] op_sel:[0,1,0] op_sel_hi:[1,0,1]
	v_pk_fma_f32 v[196:197], v[52:53], v[154:155], v[196:197] op_sel:[0,1,0] op_sel_hi:[1,0,1]
	v_pk_fma_f32 v[198:199], v[52:53], v[170:171], v[198:199] op_sel:[0,1,0] op_sel_hi:[1,0,1]
	v_pk_fma_f32 v[200:201], v[52:53], v[186:187], v[200:201] op_sel:[0,1,0] op_sel_hi:[1,0,1]
	v_pk_fma_f32 v[194:195], v[56:57], v[140:141], v[194:195] op_sel_hi:[1,0,1]
	v_pk_fma_f32 v[196:197], v[56:57], v[156:157], v[196:197] op_sel_hi:[1,0,1]
	v_pk_fma_f32 v[198:199], v[56:57], v[172:173], v[198:199] op_sel_hi:[1,0,1]
	v_pk_fma_f32 v[200:201], v[56:57], v[188:189], v[200:201] op_sel_hi:[1,0,1]
	v_pk_fma_f32 v[194:195], v[58:59], v[140:141], v[194:195] op_sel:[0,1,0] op_sel_hi:[1,1,1]
	v_pk_fma_f32 v[196:197], v[58:59], v[156:157], v[196:197] op_sel:[0,1,0] op_sel_hi:[1,1,1]
	v_pk_fma_f32 v[198:199], v[58:59], v[172:173], v[198:199] op_sel:[0,1,0] op_sel_hi:[1,1,1]
	v_pk_fma_f32 v[200:201], v[58:59], v[188:189], v[200:201] op_sel:[0,1,0] op_sel_hi:[1,1,1]
	s_waitcnt lgkmcnt(0)
	v_pk_fma_f32 v[194:195], v[62:63], v[142:143], v[194:195]
	v_pk_fma_f32 v[196:197], v[62:63], v[158:159], v[196:197]
	v_pk_fma_f32 v[198:199], v[62:63], v[174:175], v[198:199]
	v_pk_fma_f32 v[200:201], v[62:63], v[190:191], v[200:201]
	v_pk_fma_f32 v[194:195], v[60:61], v[142:143], v[194:195] op_sel:[0,1,0] op_sel_hi:[1,0,1]
	v_pk_fma_f32 v[196:197], v[60:61], v[158:159], v[196:197] op_sel:[0,1,0] op_sel_hi:[1,0,1]
	v_pk_fma_f32 v[198:199], v[60:61], v[174:175], v[198:199] op_sel:[0,1,0] op_sel_hi:[1,0,1]
	v_pk_fma_f32 v[200:201], v[60:61], v[190:191], v[200:201] op_sel:[0,1,0] op_sel_hi:[1,0,1]
	v_pk_fma_f32 v[194:195], v[64:65], v[144:145], v[194:195] op_sel_hi:[1,0,1]
	v_pk_fma_f32 v[196:197], v[64:65], v[160:161], v[196:197] op_sel_hi:[1,0,1]
	v_pk_fma_f32 v[198:199], v[64:65], v[176:177], v[198:199] op_sel_hi:[1,0,1]
	v_pk_fma_f32 v[200:201], v[64:65], v[192:193], v[200:201] op_sel_hi:[1,0,1]
	v_pk_fma_f32 v[194:195], v[66:67], v[144:145], v[194:195] op_sel:[0,1,0] op_sel_hi:[1,1,1]
	v_pk_fma_f32 v[196:197], v[66:67], v[160:161], v[196:197] op_sel:[0,1,0] op_sel_hi:[1,1,1]
	v_pk_fma_f32 v[198:199], v[66:67], v[176:177], v[198:199] op_sel:[0,1,0] op_sel_hi:[1,1,1]
	v_pk_fma_f32 v[200:201], v[66:67], v[192:193], v[200:201] op_sel:[0,1,0] op_sel_hi:[1,1,1]
	v_pk_fma_f32 v[202:203], v[70:71], v[72:73], v[194:195] op_sel:[0,1,0] op_sel_hi:[1,1,1] neg_lo:[1,0,0]
	s_nop 0
	v_pk_fma_f32 v[72:73], v[34:35], v[72:73], v[202:203] op_sel_hi:[1,0,1]
	ds_write_b64 v22, v[72:73]
	v_pk_fma_f32 v[202:203], v[70:71], v[72:73], v[196:197] op_sel:[0,1,0] op_sel_hi:[1,1,1] neg_lo:[1,0,0]
	s_nop 0
	v_pk_fma_f32 v[72:73], v[34:35], v[72:73], v[202:203] op_sel_hi:[1,0,1]
	ds_write_b64 v22, v[72:73] offset:528
	v_pk_fma_f32 v[202:203], v[70:71], v[72:73], v[198:199] op_sel:[0,1,0] op_sel_hi:[1,1,1] neg_lo:[1,0,0]
	s_nop 0
	v_pk_fma_f32 v[72:73], v[34:35], v[72:73], v[202:203] op_sel_hi:[1,0,1]
	ds_write_b64 v22, v[72:73] offset:1056
	v_pk_fma_f32 v[202:203], v[70:71], v[72:73], v[200:201] op_sel:[0,1,0] op_sel_hi:[1,1,1] neg_lo:[1,0,0]
	s_nop 0
	v_pk_fma_f32 v[72:73], v[34:35], v[72:73], v[202:203] op_sel_hi:[1,0,1]
	ds_write_b64 v22, v[72:73] offset:1584
	v_add_u32_e32 v22, 0x840, v22
	s_addk_i32 s2, 0x100
	s_cmpk_lg_i32 s2, 0x400
	s_cbranch_scc1 .LBB0_233
; DI unsigned pack2(float a, float b) { f32v2 v = {a, b}; return __builtin_bit_cast(unsigned, __builtin_convertvector(v, bf16v2)); }
; DI void s5_item(const PRef& p, int l, int b, int g) {
;     ...
;     __syncthreads();
;     f32x4 yacc = f32x4{0.f, 0.f, 0.f, 0.f};
; #pragma unroll
;     for (int s4 = 0; s4 < 4; ++s4) {
;       const float* xp = xw + (ot * 66 + 16 * s4 + oh) * 2;
;       const float4 f0 = *reinterpret_cast<const float4*>(xp), f1 = *reinterpret_cast<const float4*>(xp + 4);
;       const bf16x8 xf = __builtin_bit_cast(bf16x8, (u32x4{pack2(f0.x, f0.y), pack2(f0.z, f0.w), pack2(f1.x, f1.y), pack2(f1.z, f1.w)}));
;       yacc = __builtin_amdgcn_mfma_f32_16x16x32_bf16(cf[s4], xf, yacc, 0, 0, 0);
;     }
;     float a0 = yacc[0], a1 = yacc[1], a2 = yacc[2], a3 = yacc[3];
;     float4 u = *reinterpret_cast<const float4*>(uw + ot * 16 + oh);
;     a0 = gelu_tanh(a0 + d0 * u.x); a1 = gelu_tanh(a1 + d1 * u.y); a2 = gelu_tanh(a2 + d2 * u.z); a3 = gelu_tanh(a3 + d3 * u.w);
	s_waitcnt lgkmcnt(0)
	s_barrier
	ds_read_b128 v[22:25], v74 offset:12288
	ds_read_b128 v[26:29], v74 offset:12304
	s_waitcnt lgkmcnt(1)
	v_cvt_pk_bf16_f32 v22, v22, v23
	v_cvt_pk_bf16_f32 v23, v24, v25
	s_waitcnt lgkmcnt(0)
	v_cvt_pk_bf16_f32 v24, v26, v27
	v_cvt_pk_bf16_f32 v25, v28, v29
	ds_read_b128 v[26:29], v74 offset:12416
	ds_read_b128 v[82:85], v74 offset:12432
	v_mfma_f32_16x16x32_bf16 v[22:25], v[0:3], v[22:25], 0
	s_waitcnt lgkmcnt(1)
	v_cvt_pk_bf16_f32 v26, v26, v27
	v_cvt_pk_bf16_f32 v27, v28, v29
	s_waitcnt lgkmcnt(0)
	v_cvt_pk_bf16_f32 v28, v82, v83
	v_cvt_pk_bf16_f32 v29, v84, v85
	s_nop 1
	v_mfma_f32_16x16x32_bf16 v[22:25], v[4:7], v[26:29], v[22:25]
	ds_read_b128 v[26:29], v74 offset:12544
	ds_read_b128 v[82:85], v74 offset:12560
	s_waitcnt lgkmcnt(1)
	v_cvt_pk_bf16_f32 v26, v26, v27
	v_cvt_pk_bf16_f32 v27, v28, v29
	s_waitcnt lgkmcnt(0)
	v_cvt_pk_bf16_f32 v28, v82, v83
	v_cvt_pk_bf16_f32 v29, v84, v85
	s_nop 1
	v_mfma_f32_16x16x32_bf16 v[22:25], v[8:11], v[26:29], v[22:25]
	ds_read_b128 v[26:29], v74 offset:12672
	ds_read_b128 v[82:85], v74 offset:12688
	s_waitcnt lgkmcnt(1)
	v_cvt_pk_bf16_f32 v26, v26, v27
	v_cvt_pk_bf16_f32 v27, v28, v29
	s_waitcnt lgkmcnt(0)
	v_cvt_pk_bf16_f32 v28, v82, v83
	v_cvt_pk_bf16_f32 v29, v84, v85
	s_nop 1
	v_mfma_f32_16x16x32_bf16 v[22:25], v[12:15], v[26:29], v[22:25]
	ds_read_b128 v[26:29], v32
	s_waitcnt lgkmcnt(0)
	s_nop 5
	v_fma_f32 v22, v18, v26, v22
	v_mul_f32_e32 v26, 0x3d372713, v22
	v_mul_f32_e32 v26, v22, v26
	v_fma_f32 v26, v22, v26, v22
	v_mul_f32_e32 v26, 0x3f4c422a, v26
	v_cmp_nlt_f32_e64 s[2:3], |v26|, s78
	s_and_saveexec_b64 s[8:9], s[2:3]
	s_xor_b64 s[2:3], exec, s[8:9]
	s_cbranch_execz .LBB0_236
	v_add_f32_e64 v75, |v26|, |v26|
	v_mul_f32_e32 v76, 0x3fb8aa3b, v75
	v_rndne_f32_e32 v77, v76
	v_sub_f32_e32 v81, v76, v77
	v_fma_f32 v76, v75, s38, -v76
	v_fmac_f32_e32 v76, 0x32a5705f, v75
	v_add_f32_e32 v76, v81, v76
	v_cvt_i32_f32_e32 v77, v77
	v_exp_f32_e32 v76, v76
	v_cmp_ngt_f32_e32 vcc, s39, v75
	v_ldexp_f32 v76, v76, v77
	s_nop 0
	v_cndmask_b32_e32 v76, 0, v76, vcc
	v_cmp_nlt_f32_e32 vcc, s74, v75
	s_nop 1
	v_cndmask_b32_e32 v75, v240, v76, vcc
	v_add_f32_e32 v75, 1.0, v75
	v_rcp_f32_e32 v75, v75
	s_nop 0
	v_fma_f32 v75, v75, -2.0, 1.0
